# v20 with the FFN-up epilogue alignment pad moved into a branch-skipped region (no executed pad nops)
# speedup vs baseline: 1.0034x; 1.0034x over previous
.LBB0_1161:
	s_branch .Lmy_pad3
	s_nop 0
	s_nop 0
	s_nop 0
	s_nop 0
	s_nop 0
	s_nop 0
	s_nop 0
	s_nop 0
	s_nop 0
	s_nop 0
	s_nop 0
	s_nop 0
	s_nop 0
	s_nop 0
	s_nop 0
	s_nop 0
	s_nop 0
	s_nop 0
	s_nop 0
	s_nop 0
	s_nop 0
	s_nop 0
	s_nop 0
	s_nop 0
	s_nop 0
	s_nop 0
	s_nop 0
	s_nop 0
	s_nop 0
	s_nop 0
	s_nop 0
	s_nop 0
	s_nop 0
	s_nop 0
	s_nop 0
	s_nop 0
	s_nop 0
	s_nop 0
	s_nop 0
	s_nop 0
.Lmy_pad3:
	s_lshl_b32 s2, s60, 7
	v_cmp_gt_i32_e32 vcc, 15, v190
	s_mov_b64 s[60:61], -1
	s_and_saveexec_b64 s[34:35], vcc
	v_cmp_eq_u32_e32 vcc, 0, v190
	s_orn2_b64 s[60:61], vcc, exec
	s_or_b64 exec, exec, s[34:35]
	s_and_saveexec_b64 s[34:35], s[60:61]
	v_readlane_b32 s88, v253, 7
	v_readlane_b32 s89, v253, 8
	s_cbranch_execz .LBB0_1165
	v_cndmask_b32_e64 v135, v117, v129, s[48:49]
	v_cndmask_b32_e64 v134, v116, v128, s[48:49]
	v_cndmask_b32_e64 v133, v115, v127, s[48:49]
	v_cndmask_b32_e64 v132, v114, v126, s[48:49]
	ds_write_b128 v215, v[132:135]
	v_cndmask_b32_e64 v135, v47, v59, s[48:49]
	v_cndmask_b32_e64 v134, v46, v58, s[48:49]
	v_cndmask_b32_e64 v133, v45, v57, s[48:49]
	v_cndmask_b32_e64 v132, v44, v56, s[48:49]
	ds_write_b128 v215, v[132:135] offset:16
	v_cndmask_b32_e64 v135, v101, v113, s[48:49]
	v_cndmask_b32_e64 v134, v100, v112, s[48:49]
	v_cndmask_b32_e64 v133, v99, v111, s[48:49]
	v_cndmask_b32_e64 v132, v98, v110, s[48:49]
	ds_write_b128 v215, v[132:135] offset:32
	v_cndmask_b32_e64 v135, v35, v43, s[48:49]
	v_cndmask_b32_e64 v134, v34, v42, s[48:49]
	v_cndmask_b32_e64 v133, v33, v41, s[48:49]
	v_cndmask_b32_e64 v132, v32, v40, s[48:49]
	ds_write_b128 v215, v[132:135] offset:48
	v_cndmask_b32_e64 v135, v83, v95, s[48:49]
	v_cndmask_b32_e64 v134, v82, v94, s[48:49]
	v_cndmask_b32_e64 v133, v81, v93, s[48:49]
	v_cndmask_b32_e64 v132, v80, v92, s[48:49]
	ds_write_b128 v216, v[132:135]
	v_cndmask_b32_e64 v135, v23, v27, s[48:49]
	v_cndmask_b32_e64 v134, v22, v26, s[48:49]
	v_cndmask_b32_e64 v133, v21, v25, s[48:49]
	v_cndmask_b32_e64 v132, v20, v24, s[48:49]
	ds_write_b128 v216, v[132:135] offset:16
	v_cndmask_b32_e64 v135, v67, v79, s[48:49]
	v_cndmask_b32_e64 v134, v66, v78, s[48:49]
	v_cndmask_b32_e64 v133, v65, v77, s[48:49]
	v_cndmask_b32_e64 v132, v64, v76, s[48:49]
	ds_write_b128 v216, v[132:135] offset:32
	v_cndmask_b32_e64 v135, v7, v15, s[48:49]
	v_cndmask_b32_e64 v134, v6, v14, s[48:49]
	v_cndmask_b32_e64 v133, v5, v13, s[48:49]
	v_cndmask_b32_e64 v132, v4, v12, s[48:49]
	ds_write_b128 v216, v[132:135] offset:48
